# combined build + scale/SwiGLU epilogues fetch the next unit's ssq partials under the current unit's math
# baseline (speedup 1.0000x reference)
; __device__ __forceinline__ unsigned cvt_pk_bf16(float lo, float hi) { unsigned r; asm volatile("v_cvt_pk_bf16_f32 %0, %1, %2" : "=v"(r) : "v"(lo), "v"(hi)); return r; }
;     __device__ __forceinline__ void operator()(const f32x4 (&acc)[2][2][4][2], const Unit& u, int wr, int wc, int fr, int fq) const {
;     ...
;             for (int m = 0; m < 4; ++m) { const int row = row0 + ai * HALF + m * 16; const f32x4 q0 = *(const f32x4*)(ssq + (size_t)row * 16), q1 = *(const f32x4*)(ssq + (size_t)row * 16 + 4), q2 = *(const f32x4*)(ssq + (size_t)row * 16 + 8), q3 = *(const f32x4*)(ssq + (size_t)row * 16 + 12);
;                 const float rs = rsqrtf(((((q0[0] + q0[1]) + (q0[2] + q0[3])) + ((q1[0] + q1[1]) + (q1[2] + q1[3]))) + (((q2[0] + q2[1]) + (q2[2] + q2[3])) + ((q3[0] + q3[1]) + (q3[2] + q3[3])))) * (1.0f / 1024.0f) + 1e-6f);
;                 float a[8];
; #pragma unroll
;                 for (int n = 0; n < 2; ++n)
; #pragma unroll
;                     for (int j = 0; j < 4; ++j) { const float g = acc[ai][0][m][n][j] * rs, up = acc[ai][1][m][n][j] * rs; a[4 * n + j] = g * up * __builtin_amdgcn_rcpf(1.0f + __expf(-g)); }
;                 u32x4 w; w.x = cvt_pk_bf16(a[0], a[1]); w.y = cvt_pk_bf16(a[2], a[3]); w.z = cvt_pk_bf16(a[4], a[5]); w.w = cvt_pk_bf16(a[6], a[7]);
;                 *(u32x4*)(O + (size_t)row * ldc + col0) = w; }
.Lsw_nonext1:
	v_lshl_add_u32 v192, s55, 8, v147
	s_movk_i32 s21, 0x1600
	v_lshl_or_b32 v231, s54, 7, v149
	v_lshlrev_b32_e32 v231, 1, v231
	v_mad_u32_u24 v184, v192, s21, v231
	v_add_u32_e32 v185, 0x16000, v184
	v_add_u32_e32 v186, 0x16000, v185
	v_add_u32_e32 v187, 0x16000, v186
	v_add_u32_e32 v188, 0xb0000, v184
	v_add_u32_e32 v189, 0xb0000, v185
	v_add_u32_e32 v190, 0xb0000, v186
	v_add_u32_e32 v191, 0xb0000, v187
	v_mov_b32_e32 v236, 1.0
	v_mul_f32_e32 v232, 0xbfb8aa3b, v242
	v_mul_f32_e32 v234, v242, v242
	v_pk_mul_f32 v[124:125], v[128:129], v[124:125]
	v_pk_mul_f32 v[126:127], v[130:131], v[126:127]
	v_pk_mul_f32 v[116:117], v[120:121], v[116:117]
	v_pk_mul_f32 v[118:119], v[122:123], v[118:119]
	v_pk_mul_f32 v[128:129], v[128:129], v[232:233] op_sel_hi:[1,0]
	v_pk_mul_f32 v[130:131], v[130:131], v[232:233] op_sel_hi:[1,0]
	v_pk_mul_f32 v[120:121], v[120:121], v[232:233] op_sel_hi:[1,0]
	v_pk_mul_f32 v[122:123], v[122:123], v[232:233] op_sel_hi:[1,0]
	v_pk_mul_f32 v[124:125], v[124:125], v[234:235] op_sel_hi:[1,0]
	v_pk_mul_f32 v[126:127], v[126:127], v[234:235] op_sel_hi:[1,0]
	v_pk_mul_f32 v[116:117], v[116:117], v[234:235] op_sel_hi:[1,0]
	v_pk_mul_f32 v[118:119], v[118:119], v[234:235] op_sel_hi:[1,0]
	v_exp_f32_e32 v128, v128
	v_exp_f32_e32 v129, v129
	v_exp_f32_e32 v130, v130
	v_exp_f32_e32 v131, v131
	v_exp_f32_e32 v120, v120
	v_exp_f32_e32 v121, v121
	v_exp_f32_e32 v122, v122
	v_exp_f32_e32 v123, v123
	v_pk_add_f32 v[128:129], v[128:129], v[236:237] op_sel_hi:[1,0]
	v_pk_add_f32 v[130:131], v[130:131], v[236:237] op_sel_hi:[1,0]
	v_pk_add_f32 v[120:121], v[120:121], v[236:237] op_sel_hi:[1,0]
	v_pk_add_f32 v[122:123], v[122:123], v[236:237] op_sel_hi:[1,0]
	v_rcp_f32_e32 v128, v128
	v_rcp_f32_e32 v129, v129
	v_rcp_f32_e32 v130, v130
	v_rcp_f32_e32 v131, v131
	v_rcp_f32_e32 v120, v120
	v_rcp_f32_e32 v121, v121
	v_rcp_f32_e32 v122, v122
	v_rcp_f32_e32 v123, v123
	v_pk_mul_f32 v[128:129], v[124:125], v[128:129]
	v_pk_mul_f32 v[130:131], v[126:127], v[130:131]
	v_pk_mul_f32 v[120:121], v[116:117], v[120:121]
	v_pk_mul_f32 v[122:123], v[118:119], v[122:123]
	v_cvt_pk_bf16_f32 v128, v128, v129
	v_cvt_pk_bf16_f32 v129, v130, v131
	v_cvt_pk_bf16_f32 v130, v120, v121
	v_cvt_pk_bf16_f32 v131, v122, v123
	global_store_dwordx4 v184, v[128:131], s[28:29]
	v_mul_f32_e32 v232, 0xbfb8aa3b, v243
	v_mul_f32_e32 v234, v243, v243
	v_pk_mul_f32 v[108:109], v[112:113], v[108:109]
	v_pk_mul_f32 v[110:111], v[114:115], v[110:111]
	v_pk_mul_f32 v[100:101], v[104:105], v[100:101]
	v_pk_mul_f32 v[102:103], v[106:107], v[102:103]
	v_pk_mul_f32 v[112:113], v[112:113], v[232:233] op_sel_hi:[1,0]
	v_pk_mul_f32 v[114:115], v[114:115], v[232:233] op_sel_hi:[1,0]
	v_pk_mul_f32 v[104:105], v[104:105], v[232:233] op_sel_hi:[1,0]
	v_pk_mul_f32 v[106:107], v[106:107], v[232:233] op_sel_hi:[1,0]
	v_pk_mul_f32 v[108:109], v[108:109], v[234:235] op_sel_hi:[1,0]
	v_pk_mul_f32 v[110:111], v[110:111], v[234:235] op_sel_hi:[1,0]
	v_pk_mul_f32 v[100:101], v[100:101], v[234:235] op_sel_hi:[1,0]
	v_pk_mul_f32 v[102:103], v[102:103], v[234:235] op_sel_hi:[1,0]
	v_exp_f32_e32 v112, v112
	v_exp_f32_e32 v113, v113
	v_exp_f32_e32 v114, v114
	v_exp_f32_e32 v115, v115
	v_exp_f32_e32 v104, v104
	v_exp_f32_e32 v105, v105
	v_exp_f32_e32 v106, v106
	v_exp_f32_e32 v107, v107
	v_pk_add_f32 v[112:113], v[112:113], v[236:237] op_sel_hi:[1,0]
	v_pk_add_f32 v[114:115], v[114:115], v[236:237] op_sel_hi:[1,0]
	v_pk_add_f32 v[104:105], v[104:105], v[236:237] op_sel_hi:[1,0]
	v_pk_add_f32 v[106:107], v[106:107], v[236:237] op_sel_hi:[1,0]
	v_rcp_f32_e32 v112, v112
	v_rcp_f32_e32 v113, v113
	v_rcp_f32_e32 v114, v114
	v_rcp_f32_e32 v115, v115
	v_rcp_f32_e32 v104, v104
	v_rcp_f32_e32 v105, v105
	v_rcp_f32_e32 v106, v106
	v_rcp_f32_e32 v107, v107
	v_pk_mul_f32 v[112:113], v[108:109], v[112:113]
	v_pk_mul_f32 v[114:115], v[110:111], v[114:115]
	v_pk_mul_f32 v[104:105], v[100:101], v[104:105]
	v_pk_mul_f32 v[106:107], v[102:103], v[106:107]
	v_cvt_pk_bf16_f32 v112, v112, v113
	v_cvt_pk_bf16_f32 v113, v114, v115
	v_cvt_pk_bf16_f32 v114, v104, v105
	v_cvt_pk_bf16_f32 v115, v106, v107
	global_store_dwordx4 v185, v[112:115], s[28:29]
	v_mul_f32_e32 v232, 0xbfb8aa3b, v244
	v_mul_f32_e32 v234, v244, v244
	v_pk_mul_f32 v[92:93], v[96:97], v[92:93]
	v_pk_mul_f32 v[94:95], v[98:99], v[94:95]
	v_pk_mul_f32 v[84:85], v[88:89], v[84:85]
	v_pk_mul_f32 v[86:87], v[90:91], v[86:87]
	v_pk_mul_f32 v[96:97], v[96:97], v[232:233] op_sel_hi:[1,0]
	v_pk_mul_f32 v[98:99], v[98:99], v[232:233] op_sel_hi:[1,0]
	v_pk_mul_f32 v[88:89], v[88:89], v[232:233] op_sel_hi:[1,0]
	v_pk_mul_f32 v[90:91], v[90:91], v[232:233] op_sel_hi:[1,0]
	v_pk_mul_f32 v[92:93], v[92:93], v[234:235] op_sel_hi:[1,0]
	v_pk_mul_f32 v[94:95], v[94:95], v[234:235] op_sel_hi:[1,0]
	v_pk_mul_f32 v[84:85], v[84:85], v[234:235] op_sel_hi:[1,0]
	v_pk_mul_f32 v[86:87], v[86:87], v[234:235] op_sel_hi:[1,0]
	v_exp_f32_e32 v96, v96
	v_exp_f32_e32 v97, v97
	v_exp_f32_e32 v98, v98
	v_exp_f32_e32 v99, v99
	v_exp_f32_e32 v88, v88
	v_exp_f32_e32 v89, v89
	v_exp_f32_e32 v90, v90
	v_exp_f32_e32 v91, v91
	v_pk_add_f32 v[96:97], v[96:97], v[236:237] op_sel_hi:[1,0]
	v_pk_add_f32 v[98:99], v[98:99], v[236:237] op_sel_hi:[1,0]
	v_pk_add_f32 v[88:89], v[88:89], v[236:237] op_sel_hi:[1,0]
	v_pk_add_f32 v[90:91], v[90:91], v[236:237] op_sel_hi:[1,0]
	v_rcp_f32_e32 v96, v96
	v_rcp_f32_e32 v97, v97
	v_rcp_f32_e32 v98, v98
	v_rcp_f32_e32 v99, v99
	v_rcp_f32_e32 v88, v88
	v_rcp_f32_e32 v89, v89
	v_rcp_f32_e32 v90, v90
	v_rcp_f32_e32 v91, v91
	v_pk_mul_f32 v[96:97], v[92:93], v[96:97]
	v_pk_mul_f32 v[98:99], v[94:95], v[98:99]
	v_pk_mul_f32 v[88:89], v[84:85], v[88:89]
; __device__ __forceinline__ unsigned cvt_pk_bf16(float lo, float hi) { unsigned r; asm volatile("v_cvt_pk_bf16_f32 %0, %1, %2" : "=v"(r) : "v"(lo), "v"(hi)); return r; }
;     __device__ __forceinline__ void operator()(const f32x4 (&acc)[2][2][4][2], const Unit& u, int wr, int wc, int fr, int fq) const {
;     ...
;             for (int m = 0; m < 4; ++m) { const int row = row0 + ai * HALF + m * 16; const f32x4 q0 = *(const f32x4*)(ssq + (size_t)row * 16), q1 = *(const f32x4*)(ssq + (size_t)row * 16 + 4), q2 = *(const f32x4*)(ssq + (size_t)row * 16 + 8), q3 = *(const f32x4*)(ssq + (size_t)row * 16 + 12);
;                 const float rs = rsqrtf(((((q0[0] + q0[1]) + (q0[2] + q0[3])) + ((q1[0] + q1[1]) + (q1[2] + q1[3]))) + (((q2[0] + q2[1]) + (q2[2] + q2[3])) + ((q3[0] + q3[1]) + (q3[2] + q3[3])))) * (1.0f / 1024.0f) + 1e-6f);
;                 float a[8];
; #pragma unroll
;                 for (int n = 0; n < 2; ++n)
; #pragma unroll
;                     for (int j = 0; j < 4; ++j) { const float g = acc[ai][0][m][n][j] * rs, up = acc[ai][1][m][n][j] * rs; a[4 * n + j] = g * up * __builtin_amdgcn_rcpf(1.0f + __expf(-g)); }
;                 u32x4 w; w.x = cvt_pk_bf16(a[0], a[1]); w.y = cvt_pk_bf16(a[2], a[3]); w.z = cvt_pk_bf16(a[4], a[5]); w.w = cvt_pk_bf16(a[6], a[7]);
;                 *(u32x4*)(O + (size_t)row * ldc + col0) = w; }
	v_pk_mul_f32 v[90:91], v[86:87], v[90:91]
	v_cvt_pk_bf16_f32 v96, v96, v97
	v_cvt_pk_bf16_f32 v97, v98, v99
	v_cvt_pk_bf16_f32 v98, v88, v89
	v_cvt_pk_bf16_f32 v99, v90, v91
	global_store_dwordx4 v186, v[96:99], s[28:29]
	v_mul_f32_e32 v232, 0xbfb8aa3b, v245
	v_mul_f32_e32 v234, v245, v245
	v_pk_mul_f32 v[76:77], v[80:81], v[76:77]
	v_pk_mul_f32 v[78:79], v[82:83], v[78:79]
	v_pk_mul_f32 v[68:69], v[72:73], v[68:69]
	v_pk_mul_f32 v[70:71], v[74:75], v[70:71]
	v_pk_mul_f32 v[80:81], v[80:81], v[232:233] op_sel_hi:[1,0]
	v_pk_mul_f32 v[82:83], v[82:83], v[232:233] op_sel_hi:[1,0]
	v_pk_mul_f32 v[72:73], v[72:73], v[232:233] op_sel_hi:[1,0]
	v_pk_mul_f32 v[74:75], v[74:75], v[232:233] op_sel_hi:[1,0]
	v_pk_mul_f32 v[76:77], v[76:77], v[234:235] op_sel_hi:[1,0]
	v_pk_mul_f32 v[78:79], v[78:79], v[234:235] op_sel_hi:[1,0]
	v_pk_mul_f32 v[68:69], v[68:69], v[234:235] op_sel_hi:[1,0]
	v_pk_mul_f32 v[70:71], v[70:71], v[234:235] op_sel_hi:[1,0]
	v_exp_f32_e32 v80, v80
	v_exp_f32_e32 v81, v81
	v_exp_f32_e32 v82, v82
	v_exp_f32_e32 v83, v83
	v_exp_f32_e32 v72, v72
	v_exp_f32_e32 v73, v73
	v_exp_f32_e32 v74, v74
	v_exp_f32_e32 v75, v75
	v_pk_add_f32 v[80:81], v[80:81], v[236:237] op_sel_hi:[1,0]
	v_pk_add_f32 v[82:83], v[82:83], v[236:237] op_sel_hi:[1,0]
	v_pk_add_f32 v[72:73], v[72:73], v[236:237] op_sel_hi:[1,0]
	v_pk_add_f32 v[74:75], v[74:75], v[236:237] op_sel_hi:[1,0]
	v_rcp_f32_e32 v80, v80
	v_rcp_f32_e32 v81, v81
	v_rcp_f32_e32 v82, v82
	v_rcp_f32_e32 v83, v83
	v_rcp_f32_e32 v72, v72
	v_rcp_f32_e32 v73, v73
	v_rcp_f32_e32 v74, v74
	v_rcp_f32_e32 v75, v75
	v_pk_mul_f32 v[80:81], v[76:77], v[80:81]
	v_pk_mul_f32 v[82:83], v[78:79], v[82:83]
	v_pk_mul_f32 v[72:73], v[68:69], v[72:73]
	v_pk_mul_f32 v[74:75], v[70:71], v[74:75]
	v_cvt_pk_bf16_f32 v80, v80, v81
	v_cvt_pk_bf16_f32 v81, v82, v83
	v_cvt_pk_bf16_f32 v82, v72, v73
	v_cvt_pk_bf16_f32 v83, v74, v75
	global_store_dwordx4 v187, v[80:83], s[28:29]
	v_mul_f32_e32 v232, 0xbfb8aa3b, v246
	v_mul_f32_e32 v234, v246, v246
	v_pk_mul_f32 v[60:61], v[64:65], v[60:61]
	v_pk_mul_f32 v[62:63], v[66:67], v[62:63]
	v_pk_mul_f32 v[52:53], v[56:57], v[52:53]
	v_pk_mul_f32 v[54:55], v[58:59], v[54:55]
	v_pk_mul_f32 v[64:65], v[64:65], v[232:233] op_sel_hi:[1,0]
	v_pk_mul_f32 v[66:67], v[66:67], v[232:233] op_sel_hi:[1,0]
	v_pk_mul_f32 v[56:57], v[56:57], v[232:233] op_sel_hi:[1,0]
	v_pk_mul_f32 v[58:59], v[58:59], v[232:233] op_sel_hi:[1,0]
	v_pk_mul_f32 v[60:61], v[60:61], v[234:235] op_sel_hi:[1,0]
	v_pk_mul_f32 v[62:63], v[62:63], v[234:235] op_sel_hi:[1,0]
	v_pk_mul_f32 v[52:53], v[52:53], v[234:235] op_sel_hi:[1,0]
	v_pk_mul_f32 v[54:55], v[54:55], v[234:235] op_sel_hi:[1,0]
	v_exp_f32_e32 v64, v64
	v_exp_f32_e32 v65, v65
	v_exp_f32_e32 v66, v66
	v_exp_f32_e32 v67, v67
	v_exp_f32_e32 v56, v56
	v_exp_f32_e32 v57, v57
	v_exp_f32_e32 v58, v58
	v_exp_f32_e32 v59, v59
	v_pk_add_f32 v[64:65], v[64:65], v[236:237] op_sel_hi:[1,0]
	v_pk_add_f32 v[66:67], v[66:67], v[236:237] op_sel_hi:[1,0]
	v_pk_add_f32 v[56:57], v[56:57], v[236:237] op_sel_hi:[1,0]
	v_pk_add_f32 v[58:59], v[58:59], v[236:237] op_sel_hi:[1,0]
	v_rcp_f32_e32 v64, v64
	v_rcp_f32_e32 v65, v65
	v_rcp_f32_e32 v66, v66
	v_rcp_f32_e32 v67, v67
	v_rcp_f32_e32 v56, v56
	v_rcp_f32_e32 v57, v57
	v_rcp_f32_e32 v58, v58
	v_rcp_f32_e32 v59, v59
	v_pk_mul_f32 v[64:65], v[60:61], v[64:65]
	v_pk_mul_f32 v[66:67], v[62:63], v[66:67]
	v_pk_mul_f32 v[56:57], v[52:53], v[56:57]
	v_pk_mul_f32 v[58:59], v[54:55], v[58:59]
	v_cvt_pk_bf16_f32 v64, v64, v65
	v_cvt_pk_bf16_f32 v65, v66, v67
	v_cvt_pk_bf16_f32 v66, v56, v57
	v_cvt_pk_bf16_f32 v67, v58, v59
	global_store_dwordx4 v188, v[64:67], s[28:29]
	v_mul_f32_e32 v232, 0xbfb8aa3b, v247
	v_mul_f32_e32 v234, v247, v247
	v_pk_mul_f32 v[44:45], v[48:49], v[44:45]
	v_pk_mul_f32 v[46:47], v[50:51], v[46:47]
	v_pk_mul_f32 v[36:37], v[40:41], v[36:37]
	v_pk_mul_f32 v[38:39], v[42:43], v[38:39]
	v_pk_mul_f32 v[48:49], v[48:49], v[232:233] op_sel_hi:[1,0]
	v_pk_mul_f32 v[50:51], v[50:51], v[232:233] op_sel_hi:[1,0]
	v_pk_mul_f32 v[40:41], v[40:41], v[232:233] op_sel_hi:[1,0]
	v_pk_mul_f32 v[42:43], v[42:43], v[232:233] op_sel_hi:[1,0]
	v_pk_mul_f32 v[44:45], v[44:45], v[234:235] op_sel_hi:[1,0]
	v_pk_mul_f32 v[46:47], v[46:47], v[234:235] op_sel_hi:[1,0]
	v_pk_mul_f32 v[36:37], v[36:37], v[234:235] op_sel_hi:[1,0]
	v_pk_mul_f32 v[38:39], v[38:39], v[234:235] op_sel_hi:[1,0]
	v_exp_f32_e32 v48, v48
	v_exp_f32_e32 v49, v49
	v_exp_f32_e32 v50, v50
	v_exp_f32_e32 v51, v51
	v_exp_f32_e32 v40, v40
	v_exp_f32_e32 v41, v41
	v_exp_f32_e32 v42, v42
	v_exp_f32_e32 v43, v43
	v_pk_add_f32 v[48:49], v[48:49], v[236:237] op_sel_hi:[1,0]
	v_pk_add_f32 v[50:51], v[50:51], v[236:237] op_sel_hi:[1,0]
	v_pk_add_f32 v[40:41], v[40:41], v[236:237] op_sel_hi:[1,0]
	v_pk_add_f32 v[42:43], v[42:43], v[236:237] op_sel_hi:[1,0]
	v_rcp_f32_e32 v48, v48
	v_rcp_f32_e32 v49, v49
	v_rcp_f32_e32 v50, v50
	v_rcp_f32_e32 v51, v51
	v_rcp_f32_e32 v40, v40
	v_rcp_f32_e32 v41, v41
	v_rcp_f32_e32 v42, v42
	v_rcp_f32_e32 v43, v43
	v_pk_mul_f32 v[48:49], v[44:45], v[48:49]
	v_pk_mul_f32 v[50:51], v[46:47], v[50:51]
	v_pk_mul_f32 v[40:41], v[36:37], v[40:41]
	v_pk_mul_f32 v[42:43], v[38:39], v[42:43]
	v_cvt_pk_bf16_f32 v48, v48, v49
	v_cvt_pk_bf16_f32 v49, v50, v51
	v_cvt_pk_bf16_f32 v50, v40, v41
	v_cvt_pk_bf16_f32 v51, v42, v43
	global_store_dwordx4 v189, v[48:51], s[28:29]
	v_mul_f32_e32 v232, 0xbfb8aa3b, v248
	v_mul_f32_e32 v234, v248, v248
	v_pk_mul_f32 v[28:29], v[32:33], v[28:29]
	v_pk_mul_f32 v[30:31], v[34:35], v[30:31]
	v_pk_mul_f32 v[20:21], v[24:25], v[20:21]
	v_pk_mul_f32 v[22:23], v[26:27], v[22:23]
	v_pk_mul_f32 v[32:33], v[32:33], v[232:233] op_sel_hi:[1,0]
; __device__ __forceinline__ unsigned cvt_pk_bf16(float lo, float hi) { unsigned r; asm volatile("v_cvt_pk_bf16_f32 %0, %1, %2" : "=v"(r) : "v"(lo), "v"(hi)); return r; }
;     __device__ __forceinline__ void operator()(const f32x4 (&acc)[2][2][4][2], const Unit& u, int wr, int wc, int fr, int fq) const {
;     ...
;             for (int m = 0; m < 4; ++m) { const int row = row0 + ai * HALF + m * 16; const f32x4 q0 = *(const f32x4*)(ssq + (size_t)row * 16), q1 = *(const f32x4*)(ssq + (size_t)row * 16 + 4), q2 = *(const f32x4*)(ssq + (size_t)row * 16 + 8), q3 = *(const f32x4*)(ssq + (size_t)row * 16 + 12);
;                 const float rs = rsqrtf(((((q0[0] + q0[1]) + (q0[2] + q0[3])) + ((q1[0] + q1[1]) + (q1[2] + q1[3]))) + (((q2[0] + q2[1]) + (q2[2] + q2[3])) + ((q3[0] + q3[1]) + (q3[2] + q3[3])))) * (1.0f / 1024.0f) + 1e-6f);
;                 float a[8];
; #pragma unroll
;                 for (int n = 0; n < 2; ++n)
; #pragma unroll
;                     for (int j = 0; j < 4; ++j) { const float g = acc[ai][0][m][n][j] * rs, up = acc[ai][1][m][n][j] * rs; a[4 * n + j] = g * up * __builtin_amdgcn_rcpf(1.0f + __expf(-g)); }
;                 u32x4 w; w.x = cvt_pk_bf16(a[0], a[1]); w.y = cvt_pk_bf16(a[2], a[3]); w.z = cvt_pk_bf16(a[4], a[5]); w.w = cvt_pk_bf16(a[6], a[7]);
;                 *(u32x4*)(O + (size_t)row * ldc + col0) = w; }
	v_pk_mul_f32 v[34:35], v[34:35], v[232:233] op_sel_hi:[1,0]
	v_pk_mul_f32 v[24:25], v[24:25], v[232:233] op_sel_hi:[1,0]
	v_pk_mul_f32 v[26:27], v[26:27], v[232:233] op_sel_hi:[1,0]
	v_pk_mul_f32 v[28:29], v[28:29], v[234:235] op_sel_hi:[1,0]
	v_pk_mul_f32 v[30:31], v[30:31], v[234:235] op_sel_hi:[1,0]
	v_pk_mul_f32 v[20:21], v[20:21], v[234:235] op_sel_hi:[1,0]
	v_pk_mul_f32 v[22:23], v[22:23], v[234:235] op_sel_hi:[1,0]
	v_exp_f32_e32 v32, v32
	v_exp_f32_e32 v33, v33
	v_exp_f32_e32 v34, v34
	v_exp_f32_e32 v35, v35
	v_exp_f32_e32 v24, v24
	v_exp_f32_e32 v25, v25
	v_exp_f32_e32 v26, v26
	v_exp_f32_e32 v27, v27
	v_pk_add_f32 v[32:33], v[32:33], v[236:237] op_sel_hi:[1,0]
	v_pk_add_f32 v[34:35], v[34:35], v[236:237] op_sel_hi:[1,0]
	v_pk_add_f32 v[24:25], v[24:25], v[236:237] op_sel_hi:[1,0]
	v_pk_add_f32 v[26:27], v[26:27], v[236:237] op_sel_hi:[1,0]
	v_rcp_f32_e32 v32, v32
	v_rcp_f32_e32 v33, v33
	v_rcp_f32_e32 v34, v34
	v_rcp_f32_e32 v35, v35
	v_rcp_f32_e32 v24, v24
	v_rcp_f32_e32 v25, v25
	v_rcp_f32_e32 v26, v26
	v_rcp_f32_e32 v27, v27
	v_pk_mul_f32 v[32:33], v[28:29], v[32:33]
	v_pk_mul_f32 v[34:35], v[30:31], v[34:35]
	v_pk_mul_f32 v[24:25], v[20:21], v[24:25]
	v_pk_mul_f32 v[26:27], v[22:23], v[26:27]
	v_cvt_pk_bf16_f32 v32, v32, v33
	v_cvt_pk_bf16_f32 v33, v34, v35
	v_cvt_pk_bf16_f32 v34, v24, v25
	v_cvt_pk_bf16_f32 v35, v26, v27
	global_store_dwordx4 v190, v[32:35], s[28:29]
	v_mul_f32_e32 v232, 0xbfb8aa3b, v249
	v_mul_f32_e32 v234, v249, v249
	v_pk_mul_f32 v[12:13], v[16:17], v[12:13]
	v_pk_mul_f32 v[14:15], v[18:19], v[14:15]
	v_pk_mul_f32 v[4:5], v[8:9], v[4:5]
	v_pk_mul_f32 v[6:7], v[10:11], v[6:7]
	v_pk_mul_f32 v[16:17], v[16:17], v[232:233] op_sel_hi:[1,0]
	v_pk_mul_f32 v[18:19], v[18:19], v[232:233] op_sel_hi:[1,0]
	v_pk_mul_f32 v[8:9], v[8:9], v[232:233] op_sel_hi:[1,0]
	v_pk_mul_f32 v[10:11], v[10:11], v[232:233] op_sel_hi:[1,0]
	v_pk_mul_f32 v[12:13], v[12:13], v[234:235] op_sel_hi:[1,0]
	v_pk_mul_f32 v[14:15], v[14:15], v[234:235] op_sel_hi:[1,0]
	v_pk_mul_f32 v[4:5], v[4:5], v[234:235] op_sel_hi:[1,0]
	v_pk_mul_f32 v[6:7], v[6:7], v[234:235] op_sel_hi:[1,0]
	v_exp_f32_e32 v16, v16
	v_exp_f32_e32 v17, v17
	v_exp_f32_e32 v18, v18
	v_exp_f32_e32 v19, v19
	v_exp_f32_e32 v8, v8
	v_exp_f32_e32 v9, v9
	v_exp_f32_e32 v10, v10
	v_exp_f32_e32 v11, v11
	v_pk_add_f32 v[16:17], v[16:17], v[236:237] op_sel_hi:[1,0]
	v_pk_add_f32 v[18:19], v[18:19], v[236:237] op_sel_hi:[1,0]
	v_pk_add_f32 v[8:9], v[8:9], v[236:237] op_sel_hi:[1,0]
	v_pk_add_f32 v[10:11], v[10:11], v[236:237] op_sel_hi:[1,0]
	v_rcp_f32_e32 v16, v16
	v_rcp_f32_e32 v17, v17
	v_rcp_f32_e32 v18, v18
	v_rcp_f32_e32 v19, v19
	v_rcp_f32_e32 v8, v8
	v_rcp_f32_e32 v9, v9
	v_rcp_f32_e32 v10, v10
	v_rcp_f32_e32 v11, v11
	v_pk_mul_f32 v[16:17], v[12:13], v[16:17]
	v_pk_mul_f32 v[18:19], v[14:15], v[18:19]
	v_pk_mul_f32 v[8:9], v[4:5], v[8:9]
	v_pk_mul_f32 v[10:11], v[6:7], v[10:11]
	v_cvt_pk_bf16_f32 v16, v16, v17
	v_cvt_pk_bf16_f32 v17, v18, v19
	v_cvt_pk_bf16_f32 v18, v8, v9
	v_cvt_pk_bf16_f32 v19, v10, v11
	global_store_dwordx4 v191, v[16:19], s[28:29]
	s_and_b64 vcc, exec, s[2:3]
	s_cbranch_vccz .Lsw_nonext2
	s_waitcnt vmcnt(15)
	v_add_f32_e32 v154, v154, v155
	v_add_f32_e32 v194, v152, v153
	v_add_f32_e32 v194, v194, v154
	s_waitcnt vmcnt(14)
	v_add_f32_e32 v158, v158, v159
	v_add_f32_e32 v195, v156, v157
	v_add_f32_e32 v195, v195, v158
	s_waitcnt vmcnt(13)
	v_add_f32_e32 v162, v162, v163
	v_add_f32_e32 v196, v160, v161
	v_add_f32_e32 v196, v196, v162
	s_waitcnt vmcnt(12)
	v_add_f32_e32 v166, v166, v167
	v_add_f32_e32 v197, v164, v165
	v_add_f32_e32 v197, v197, v166
	s_waitcnt vmcnt(11)
	v_add_f32_e32 v170, v170, v171
	v_add_f32_e32 v204, v168, v169
	v_add_f32_e32 v204, v204, v170
	s_waitcnt vmcnt(10)
	v_add_f32_e32 v174, v174, v175
	v_add_f32_e32 v205, v172, v173
	v_add_f32_e32 v205, v205, v174
	s_waitcnt vmcnt(9)
	v_add_f32_e32 v178, v178, v179
	v_add_f32_e32 v206, v176, v177
	v_add_f32_e32 v206, v206, v178
	s_waitcnt vmcnt(8)
	v_add_f32_e32 v182, v182, v183
	v_add_f32_e32 v207, v180, v181
	v_add_f32_e32 v207, v207, v182
	ds_bpermute_b32 v220, v228, v194
	ds_bpermute_b32 v221, v228, v195
	ds_bpermute_b32 v222, v228, v196
	ds_bpermute_b32 v223, v228, v197
	ds_bpermute_b32 v224, v228, v204
	ds_bpermute_b32 v225, v228, v205
	ds_bpermute_b32 v226, v228, v206
	ds_bpermute_b32 v227, v228, v207
	s_waitcnt lgkmcnt(7)
	v_add_f32_e32 v194, v194, v220
	s_waitcnt lgkmcnt(6)
	v_add_f32_e32 v195, v195, v221
	s_waitcnt lgkmcnt(5)
	v_add_f32_e32 v196, v196, v222
	s_waitcnt lgkmcnt(4)
	v_add_f32_e32 v197, v197, v223
	s_waitcnt lgkmcnt(3)
	v_add_f32_e32 v204, v204, v224
	s_waitcnt lgkmcnt(2)
	v_add_f32_e32 v205, v205, v225
	s_waitcnt lgkmcnt(1)
	v_add_f32_e32 v206, v206, v226
	s_waitcnt lgkmcnt(0)
	v_add_f32_e32 v207, v207, v227
	ds_bpermute_b32 v220, v229, v194
	ds_bpermute_b32 v221, v229, v195
	ds_bpermute_b32 v222, v229, v196
	ds_bpermute_b32 v223, v229, v197
	ds_bpermute_b32 v224, v229, v204
	ds_bpermute_b32 v225, v229, v205
	ds_bpermute_b32 v226, v229, v206
	ds_bpermute_b32 v227, v229, v207
	s_waitcnt lgkmcnt(7)
	v_add_f32_e32 v194, v194, v220
	s_waitcnt lgkmcnt(6)
	v_add_f32_e32 v195, v195, v221
	s_waitcnt lgkmcnt(5)
	v_add_f32_e32 v196, v196, v222
	s_waitcnt lgkmcnt(4)
	v_add_f32_e32 v197, v197, v223
	s_waitcnt lgkmcnt(3)
	v_add_f32_e32 v204, v204, v224
	s_waitcnt lgkmcnt(2)
	v_add_f32_e32 v205, v205, v225
	s_waitcnt lgkmcnt(1)
	v_add_f32_e32 v206, v206, v226
	s_waitcnt lgkmcnt(0)
	v_add_f32_e32 v207, v207, v227
	v_fmamk_f32 v194, v194, 0x3a800000, v208
	v_fmamk_f32 v195, v195, 0x3a800000, v208
	v_fmamk_f32 v196, v196, 0x3a800000, v208
	v_fmamk_f32 v197, v197, 0x3a800000, v208
	v_fmamk_f32 v204, v204, 0x3a800000, v208
	v_fmamk_f32 v205, v205, 0x3a800000, v208
	v_fmamk_f32 v206, v206, 0x3a800000, v208
	v_fmamk_f32 v207, v207, 0x3a800000, v208
	v_rsq_f32_e32 v242, v194
	v_rsq_f32_e32 v243, v195
	v_rsq_f32_e32 v244, v196
	v_rsq_f32_e32 v245, v197
	v_rsq_f32_e32 v246, v204
	v_rsq_f32_e32 v247, v205
	v_rsq_f32_e32 v248, v206
	v_rsq_f32_e32 v249, v207
